# NSA window loop: LDS fragment reads of each MFMA section issued together into unused registers (fragments still needed later keep their registers)
# speedup vs baseline: 1.0058x; 1.0058x over previous
.LBB0_1223:
	s_add_i32 s6, s26, 0
	s_cmp_le_u32 s27, s54
	s_cselect_b64 s[10:11], -1, 0
	s_xor_b64 s[12:13], s[28:29], -1
	s_or_b64 s[48:49], s[10:11], s[12:13]
	v_add_u32_e32 v91, 0xfffffdfb, v110
	v_add_u32_e32 v90, 0xfffffdfa, v110
	v_add_u32_e32 v89, 0xfffffdf9, v110
	v_add_u32_e32 v88, 0xfffffddc, v110
	v_add_u32_e32 v87, 0xfffffddb, v110
	v_add_u32_e32 v86, 0xfffffdda, v110
	v_add_u32_e32 v85, 0xfffffdd9, v110
	s_mov_b64 s[52:53], -1
	s_and_b64 vcc, exec, s[48:49]
	v_cmp_ge_f32_e64 s[28:29], s76, v92
	v_add_u32_e32 v84, s6, v163
	v_add_u32_e32 v3, s6, v211
	v_add_u32_e32 v2, s6, v165
	v_add_u32_e32 v0, s6, v212
	v_cmp_lt_u32_e64 s[44:45], s77, v91
	v_cmp_lt_u32_e64 s[40:41], s77, v90
	v_cmp_lt_u32_e64 s[42:43], s77, v89
	v_cmp_lt_u32_e64 s[30:31], s77, v88
	v_cmp_lt_u32_e64 s[34:35], s77, v87
	v_cmp_lt_u32_e64 s[36:37], s77, v86
	v_cmp_lt_u32_e64 s[38:39], s77, v85
	s_cbranch_vccz .LBB0_1235
	ds_read_b128 v[134:137], v84
	ds_read_b128 v[138:141], v3
	ds_read_b128 v[142:145], v2
	ds_read_b128 v[170:173], v0
	ds_read_b128 v[174:177], v84 offset:4096
	ds_read_b128 v[182:185], v3 offset:4096
	ds_read_b128 v[186:189], v2 offset:4096
	ds_read_b128 v[206:209], v0 offset:4096
	s_waitcnt lgkmcnt(8)
	s_nop 0
	v_cndmask_b32_e64 v36, v92, 0, s[28:29]
	v_xor_b32_e32 v38, 0x80000000, v36
	v_mov_b32_e32 v39, v38
	v_mov_b32_e32 v40, v38
	v_mov_b32_e32 v41, v38
	v_add_u32_e32 v37, -4, v110
	s_movk_i32 s7, 0x200
	s_waitcnt vmcnt(3)
	s_waitcnt lgkmcnt(7)
	v_mfma_f32_16x16x32_bf16 v[42:45], v[134:137], v[4:7], v[38:41]
	v_cmp_gt_u32_e32 vcc, s7, v37
	v_add_u32_e32 v37, 0xfffffdf8, v110
	s_waitcnt vmcnt(2)
	s_waitcnt lgkmcnt(6)
	v_mfma_f32_16x16x32_bf16 v[42:45], v[138:141], v[8:11], v[42:45]
	s_nop 0
	s_nop 0
	s_nop 0
	s_waitcnt lgkmcnt(5)
	v_mfma_f32_16x16x32_bf16 v[46:49], v[142:145], v[4:7], v[38:41]
	s_nop 0
	s_waitcnt lgkmcnt(4)
	v_mfma_f32_16x16x32_bf16 v[46:49], v[170:173], v[8:11], v[46:49]
	s_nop 0
	s_nop 0
	s_nop 0
	s_waitcnt lgkmcnt(3)
	v_mfma_f32_16x16x32_bf16 v[50:53], v[174:177], v[4:7], v[38:41]
	s_nop 0
	s_waitcnt lgkmcnt(2)
	v_mfma_f32_16x16x32_bf16 v[60:63], v[182:185], v[8:11], v[50:53]
	s_nop 5
	s_nop 0
	s_nop 0
	v_cndmask_b32_e64 v61, v201, v61, s[34:35]
	s_nop 0
	s_waitcnt lgkmcnt(1)
	v_mfma_f32_16x16x32_bf16 v[38:41], v[186:189], v[4:7], v[38:41]
	v_cndmask_b32_e32 v52, v201, v42, vcc
	v_cmp_lt_u32_e32 vcc, s77, v37
	v_add_u32_e32 v37, 0xfffffdf7, v110
	s_nop 0
	s_waitcnt lgkmcnt(0)
	v_mfma_f32_16x16x32_bf16 v[38:41], v[206:209], v[8:11], v[38:41]
	v_cndmask_b32_e32 v56, v201, v46, vcc
	v_cmp_lt_u32_e32 vcc, s77, v37
	v_add_u32_e32 v37, 0xfffffdf6, v110
	v_cndmask_b32_e64 v54, v201, v44, s[40:41]
	v_cndmask_b32_e32 v57, v201, v47, vcc
	v_cmp_lt_u32_e32 vcc, s77, v37
	v_add_u32_e32 v37, 0xfffffdf5, v110
	v_cndmask_b32_e64 v55, v201, v45, s[42:43]
	v_cndmask_b32_e32 v58, v201, v48, vcc
	v_cmp_lt_u32_e32 vcc, s77, v37
	v_add_u32_e32 v37, 0xfffffdd8, v110
	v_cndmask_b32_e64 v53, v201, v43, s[44:45]
	v_cndmask_b32_e32 v59, v201, v49, vcc
	v_cmp_lt_u32_e32 vcc, s77, v37
	v_add_u32_e32 v37, 0xfffffdd7, v110
	v_cndmask_b32_e64 v62, v201, v62, s[36:37]
	v_cndmask_b32_e32 v64, v201, v38, vcc
	v_cmp_lt_u32_e32 vcc, s77, v37
	v_add_u32_e32 v37, 0xfffffdd6, v110
	v_max_f32_e32 v38, v54, v54
	v_cndmask_b32_e32 v65, v201, v39, vcc
	v_cmp_lt_u32_e32 vcc, s77, v37
	v_add_u32_e32 v37, 0xfffffdd5, v110
	v_cndmask_b32_e64 v63, v201, v63, s[38:39]
	v_cndmask_b32_e32 v66, v201, v40, vcc
	v_cmp_lt_u32_e32 vcc, s77, v37
	v_max_f32_e32 v37, v55, v55
	v_max_f32_e32 v37, v38, v37
	v_max3_f32 v37, v52, v53, v37
	v_max3_f32 v38, v57, v58, v59
	v_cndmask_b32_e64 v60, v201, v60, s[30:31]
	v_cndmask_b32_e32 v67, v201, v41, vcc
	v_max3_f32 v37, v37, v56, v38
	v_max3_f32 v38, v61, v62, v63
	v_max3_f32 v37, v37, v60, v38
	v_max3_f32 v38, v65, v66, v67
	v_max3_f32 v37, v37, v64, v38
	v_cmp_lt_f32_e32 vcc, s76, v37
	v_cmp_lt_f32_e64 s[30:31], s82, v37
	s_nop 0
	v_cndmask_b32_e64 v38, 0, 1, vcc
	v_cndmask_b32_e64 v39, 0, 1, s[30:31]
	v_cndmask_b32_e64 v38, v39, v38, s[28:29]
	v_and_b32_e32 v38, 1, v38
	v_cmp_ne_u32_e32 vcc, 0, v38
	s_cbranch_vccz .LBB0_1247
	v_mov_b32_e32 v38, v37
	s_nop 1
	v_permlane16_swap_b32_e32 v37, v38
	v_max_f32_e32 v38, v38, v38
	v_max_f32_e32 v37, v37, v37
	v_max_f32_e32 v37, v37, v38
	v_mov_b32_e32 v38, v37
	s_nop 1
	v_permlane32_swap_b32_e32 v37, v38
	v_max_f32_e32 v38, v38, v38
	v_max_f32_e32 v37, v37, v37
	v_max_f32_e32 v37, v37, v38
	v_cmp_ge_f32_e32 vcc, s76, v37
	s_and_b64 vcc, s[28:29], vcc
	s_nop 0
	v_cndmask_b32_e64 v38, v37, 0, vcc
	v_max_f32_e32 v37, 0, v37
	v_cndmask_b32_e64 v123, v37, v38, s[28:29]
	v_exp_f32_e64 v96, -v123
	v_add_f32_e32 v36, v36, v123
	v_cndmask_b32_e32 v114, v36, v92, vcc
	v_sub_f32_e32 v95, v52, v123
	v_mul_f32_e32 v94, v93, v96
	v_pk_mul_f32 v[50:51], v[82:83], v[96:97] op_sel_hi:[1,0]
	v_pk_mul_f32 v[48:49], v[80:81], v[96:97] op_sel_hi:[1,0]
	v_pk_mul_f32 v[46:47], v[78:79], v[96:97] op_sel_hi:[1,0]
	v_pk_mul_f32 v[44:45], v[76:77], v[96:97] op_sel_hi:[1,0]
	v_pk_mul_f32 v[42:43], v[74:75], v[96:97] op_sel_hi:[1,0]
	v_pk_mul_f32 v[40:41], v[72:73], v[96:97] op_sel_hi:[1,0]
	v_pk_mul_f32 v[38:39], v[70:71], v[96:97] op_sel_hi:[1,0]
	v_pk_mul_f32 v[36:37], v[68:69], v[96:97] op_sel_hi:[1,0]
	v_sub_f32_e32 v96, v53, v123
	v_sub_f32_e32 v97, v54, v123
	v_sub_f32_e32 v98, v55, v123
	v_sub_f32_e32 v99, v56, v123
	v_sub_f32_e32 v108, v57, v123
	v_sub_f32_e32 v109, v58, v123
	v_sub_f32_e32 v115, v59, v123
	v_sub_f32_e32 v116, v60, v123
	v_sub_f32_e32 v117, v61, v123
	v_sub_f32_e32 v118, v62, v123
	v_sub_f32_e32 v119, v63, v123
	v_sub_f32_e32 v120, v64, v123
	v_sub_f32_e32 v121, v65, v123
	v_sub_f32_e32 v122, v66, v123
	v_sub_f32_e32 v123, v67, v123
	s_cbranch_execnz .LBB0_1227

.LBB0_1227:
	v_exp_f32_e32 v52, v95
	v_exp_f32_e32 v54, v96
	v_exp_f32_e32 v53, v97
	v_exp_f32_e32 v55, v98
	v_exp_f32_e32 v56, v99
	v_exp_f32_e32 v58, v108
	v_exp_f32_e32 v57, v109
	v_exp_f32_e32 v59, v115
	v_exp_f32_e32 v115, v116
	v_exp_f32_e32 v128, v117
	v_exp_f32_e32 v129, v118
	v_exp_f32_e32 v130, v119
	v_pk_add_f32 v[60:61], v[52:53], v[54:55]
	v_exp_f32_e32 v98, v120
	v_exp_f32_e32 v108, v121
	v_exp_f32_e32 v124, v122
	v_exp_f32_e32 v126, v123
	v_add_f32_e32 v60, v60, v61
	v_add_f32_e32 v127, 0, v60
	v_pk_add_f32 v[60:61], v[56:57], v[58:59]
	v_add_f32_e32 v99, v115, v128
	v_pk_add_f32 v[60:61], v[60:61], v[60:61] op_sel_hi:[0,1]
	v_add_f32_e32 v109, v129, v130
	v_mov_b32_e32 v125, v61
	v_pk_add_f32 v[62:63], v[98:99], v[108:109]
	v_pk_add_f32 v[60:61], v[124:125], v[126:127]
	v_add_u32_e32 v64, s6, v215
	v_pk_add_f32 v[60:61], v[62:63], v[60:61]
	v_cvt_pk_bf16_f32 v95, v53, v55
	v_add_f32_e32 v60, v60, v61
	v_add_f32_e32 v109, v94, v60
	v_cvt_pk_bf16_f32 v94, v52, v54
	v_cvt_pk_bf16_f32 v96, v56, v58
	v_cvt_pk_bf16_f32 v97, v57, v59
	ds_read_b128 v[52:55], v64 offset:8192
	s_waitcnt lgkmcnt(1)
	ds_read_b128 v[56:59], v64 offset:10240
	s_nop 0
	ds_read_b128 v[60:63], v64 offset:12288
	s_nop 0
	ds_read_b128 v[64:67], v64 offset:14336
	s_nop 0
	v_cvt_pk_bf16_f32 v122, v98, v108
	v_add_u32_e32 v98, s6, v216
	ds_read_b128 v[174:177], v98 offset:10240
	ds_read_b128 v[182:185], v98 offset:8192
	ds_read_b128 v[186:189], v98 offset:12288
	ds_read_b128 v[206:209], v98 offset:14336
	s_nop 0
	s_waitcnt lgkmcnt(7)
	v_mfma_f32_16x16x32_bf16 v[48:51], v[52:55], v[94:97], v[48:51]
	v_cvt_pk_bf16_f32 v120, v115, v128
	v_cvt_pk_bf16_f32 v121, v129, v130
	v_cvt_pk_bf16_f32 v123, v124, v126
	s_nop 0
	s_waitcnt lgkmcnt(6)
	v_mfma_f32_16x16x32_bf16 v[44:47], v[56:59], v[94:97], v[44:47]
	s_nop 0
	s_waitcnt lgkmcnt(5)
	v_mfma_f32_16x16x32_bf16 v[116:119], v[60:63], v[94:97], v[40:43]
	s_nop 2
	s_nop 0
	s_nop 0
	s_waitcnt lgkmcnt(4)
	v_mfma_f32_16x16x32_bf16 v[94:97], v[64:67], v[94:97], v[36:39]
	s_nop 2
	s_nop 0
	s_nop 0
	s_waitcnt lgkmcnt(3)
	v_mfma_f32_16x16x32_bf16 v[40:43], v[174:177], v[120:123], v[44:47]
	s_nop 2
	s_nop 0
	s_nop 0
	s_waitcnt lgkmcnt(2)
	v_mfma_f32_16x16x32_bf16 v[36:39], v[182:185], v[120:123], v[48:51]
	s_nop 2
	s_nop 0
	s_nop 0
	s_waitcnt lgkmcnt(1)
	v_mfma_f32_16x16x32_bf16 v[44:47], v[186:189], v[120:123], v[116:119]
	s_nop 0
	s_waitcnt lgkmcnt(0)
	v_mfma_f32_16x16x32_bf16 v[48:51], v[206:209], v[120:123], v[94:97]

.LBB0_1229:
	ds_read_b128 v[134:137], v84
	ds_read_b128 v[138:141], v3
	ds_read_b128 v[142:145], v2
	ds_read_b128 v[170:173], v0
	ds_read_b128 v[174:177], v84 offset:4096
	ds_read_b128 v[182:185], v3 offset:4096
	ds_read_b128 v[186:189], v2 offset:4096
	ds_read_b128 v[206:209], v0 offset:4096
	s_waitcnt lgkmcnt(8)
	s_nop 0
	s_nop 0
	s_nop 0
	v_cndmask_b32_e64 v68, v112, 0, s[28:29]
	v_xor_b32_e32 v78, 0x80000000, v68
	v_mov_b32_e32 v79, v78
	v_mov_b32_e32 v80, v78
	v_mov_b32_e32 v81, v78
	s_movk_i32 s7, 0x200
	v_cmp_gt_u32_e32 vcc, s7, v110
	s_waitcnt vmcnt(1)
	s_waitcnt lgkmcnt(7)
	v_mfma_f32_16x16x32_bf16 v[70:73], v[134:137], v[12:15], v[78:81]
	v_add_u32_e32 v69, 0xfffffdff, v110
	s_nop 0
	s_waitcnt lgkmcnt(5)
	v_mfma_f32_16x16x32_bf16 v[74:77], v[142:145], v[12:15], v[78:81]
	s_waitcnt vmcnt(0)
	v_mfma_f32_16x16x32_bf16 v[70:73], v[138:141], v[16:19], v[70:73]
	s_nop 0
	s_nop 0
	s_nop 0
	s_waitcnt lgkmcnt(4)
	v_mfma_f32_16x16x32_bf16 v[74:77], v[170:173], v[16:19], v[74:77]
	s_nop 0
	s_nop 0
	s_nop 0
	s_waitcnt lgkmcnt(3)
	v_mfma_f32_16x16x32_bf16 v[124:127], v[174:177], v[12:15], v[78:81]
	v_cndmask_b32_e32 v92, v201, v70, vcc
	v_cmp_lt_u32_e32 vcc, s77, v69
	v_add_u32_e32 v69, 0xfffffdfe, v110
	s_nop 0
	s_waitcnt lgkmcnt(2)
	v_mfma_f32_16x16x32_bf16 v[116:119], v[182:185], v[16:19], v[124:127]
	v_cndmask_b32_e32 v93, v201, v71, vcc
	v_cmp_lt_u32_e32 vcc, s77, v69
	v_add_u32_e32 v69, 0xfffffdfd, v110
	s_nop 0
	s_waitcnt lgkmcnt(1)
	v_mfma_f32_16x16x32_bf16 v[78:81], v[186:189], v[12:15], v[78:81]
	v_cndmask_b32_e32 v94, v201, v72, vcc
	v_cmp_lt_u32_e32 vcc, s77, v69
	v_add_u32_e32 v69, 0xfffffdfc, v110
	s_nop 0
	s_waitcnt lgkmcnt(0)
	v_mfma_f32_16x16x32_bf16 v[78:81], v[206:209], v[16:19], v[78:81]
	v_cndmask_b32_e32 v95, v201, v73, vcc
	v_cmp_lt_u32_e32 vcc, s77, v69
	v_add_u32_e32 v69, 0xfffffde0, v110
	v_max_f32_e32 v70, v94, v94
	v_cndmask_b32_e32 v96, v201, v74, vcc
	v_cmp_lt_u32_e32 vcc, s77, v91
	s_nop 1
	v_cndmask_b32_e32 v91, v201, v75, vcc
	v_cmp_lt_u32_e32 vcc, s77, v90
	s_nop 1
	v_cndmask_b32_e32 v90, v201, v76, vcc
	v_cmp_lt_u32_e32 vcc, s77, v89
	s_nop 1
	v_cndmask_b32_e32 v89, v201, v77, vcc
	v_cmp_lt_u32_e32 vcc, s77, v69
	v_add_u32_e32 v69, 0xfffffddf, v110
	s_nop 0
	v_cndmask_b32_e32 v97, v201, v116, vcc
	v_cmp_lt_u32_e32 vcc, s77, v69
	v_add_u32_e32 v69, 0xfffffdde, v110
	s_nop 0
	v_cndmask_b32_e32 v98, v201, v117, vcc
	v_cmp_lt_u32_e32 vcc, s77, v69
	v_add_u32_e32 v69, 0xfffffddd, v110
	s_nop 0
	v_cndmask_b32_e32 v99, v201, v118, vcc
	v_cmp_lt_u32_e32 vcc, s77, v69
	v_max_f32_e32 v69, v95, v95
	v_max_f32_e32 v69, v70, v69
	v_cndmask_b32_e32 v108, v201, v119, vcc
	v_cmp_lt_u32_e32 vcc, s77, v88
	v_max3_f32 v69, v92, v93, v69
	v_max3_f32 v70, v91, v90, v89
	v_cndmask_b32_e32 v88, v201, v78, vcc
	v_cmp_lt_u32_e32 vcc, s77, v87
	v_max3_f32 v69, v69, v96, v70
	v_max3_f32 v70, v98, v99, v108
	v_cndmask_b32_e32 v87, v201, v79, vcc
	v_cmp_lt_u32_e32 vcc, s77, v86
	v_max3_f32 v69, v69, v97, v70
	s_nop 0
	v_cndmask_b32_e32 v86, v201, v80, vcc
	v_cmp_lt_u32_e32 vcc, s77, v85
	s_nop 1
	v_cndmask_b32_e32 v85, v201, v81, vcc
	v_max3_f32 v70, v87, v86, v85
	v_max3_f32 v69, v69, v88, v70
	v_cmp_lt_f32_e32 vcc, s76, v69
	s_nop 1
	v_cndmask_b32_e64 v70, 0, 1, vcc
	v_cmp_lt_f32_e32 vcc, s82, v69
	s_nop 1
	v_cndmask_b32_e64 v71, 0, 1, vcc
	v_cndmask_b32_e64 v70, v71, v70, s[28:29]
	v_and_b32_e32 v70, 1, v70
	v_cmp_ne_u32_e32 vcc, 0, v70
	s_cbranch_vccz .LBB0_1248
	v_mov_b32_e32 v70, v69
	s_nop 1
	v_permlane16_swap_b32_e32 v69, v70
	v_max_f32_e32 v70, v70, v70
	v_max_f32_e32 v69, v69, v69
	v_max_f32_e32 v69, v69, v70
	v_mov_b32_e32 v70, v69
	s_nop 1
	v_permlane32_swap_b32_e32 v69, v70
	v_max_f32_e32 v70, v70, v70
	v_max_f32_e32 v69, v69, v69
	v_max_f32_e32 v69, v69, v70
	v_cmp_ge_f32_e32 vcc, s76, v69
	s_and_b64 vcc, s[28:29], vcc
	s_nop 0
	v_cndmask_b32_e64 v70, v69, 0, vcc
	v_max_f32_e32 v69, 0, v69
	v_cndmask_b32_e64 v132, v69, v70, s[28:29]
	v_exp_f32_e64 v118, -v132
	v_add_f32_e32 v68, v68, v132
	v_cndmask_b32_e32 v115, v68, v112, vcc
	v_sub_f32_e32 v117, v92, v132
	v_mul_f32_e32 v116, v113, v118
	v_pk_mul_f32 v[82:83], v[34:35], v[118:119] op_sel_hi:[1,0]
	v_pk_mul_f32 v[80:81], v[32:33], v[118:119] op_sel_hi:[1,0]
	v_pk_mul_f32 v[78:79], v[30:31], v[118:119] op_sel_hi:[1,0]
	v_pk_mul_f32 v[76:77], v[28:29], v[118:119] op_sel_hi:[1,0]
	v_pk_mul_f32 v[74:75], v[26:27], v[118:119] op_sel_hi:[1,0]
	v_pk_mul_f32 v[72:73], v[24:25], v[118:119] op_sel_hi:[1,0]
	v_pk_mul_f32 v[70:71], v[22:23], v[118:119] op_sel_hi:[1,0]
	v_pk_mul_f32 v[68:69], v[20:21], v[118:119] op_sel_hi:[1,0]
	v_sub_f32_e32 v118, v93, v132
	v_sub_f32_e32 v119, v94, v132
	v_sub_f32_e32 v120, v95, v132
	v_sub_f32_e32 v121, v96, v132
	v_sub_f32_e32 v122, v91, v132
	v_sub_f32_e32 v123, v90, v132
	v_sub_f32_e32 v124, v89, v132
	v_sub_f32_e32 v125, v97, v132
	v_sub_f32_e32 v126, v98, v132
	v_sub_f32_e32 v127, v99, v132
	v_sub_f32_e32 v128, v108, v132
	v_sub_f32_e32 v129, v88, v132
	v_sub_f32_e32 v130, v87, v132
	v_sub_f32_e32 v131, v86, v132
	v_sub_f32_e32 v132, v85, v132
	s_cbranch_execnz .LBB0_1232

.LBB0_1232:
	v_exp_f32_e32 v86, v117
	v_exp_f32_e32 v88, v118
	v_exp_f32_e32 v87, v119
	v_exp_f32_e32 v89, v120
	v_exp_f32_e32 v90, v121
	v_exp_f32_e32 v92, v122
	v_exp_f32_e32 v91, v123
	v_exp_f32_e32 v93, v124
	v_exp_f32_e32 v85, v125
	v_exp_f32_e32 v117, v126
	v_exp_f32_e32 v124, v127
	v_exp_f32_e32 v125, v128
	v_pk_add_f32 v[94:95], v[86:87], v[88:89]
	v_exp_f32_e32 v96, v129
	v_exp_f32_e32 v98, v130
	v_exp_f32_e32 v118, v131
	v_exp_f32_e32 v120, v132
	v_add_f32_e32 v94, v94, v95
	v_add_f32_e32 v121, 0, v94
	v_pk_add_f32 v[94:95], v[90:91], v[92:93]
	v_add_f32_e32 v97, v85, v117
	v_pk_add_f32 v[94:95], v[94:95], v[94:95] op_sel_hi:[0,1]
	v_add_f32_e32 v99, v124, v125
	v_mov_b32_e32 v119, v95
	v_pk_add_f32 v[122:123], v[96:97], v[98:99]
	v_pk_add_f32 v[94:95], v[118:119], v[120:121]
	v_cvt_pk_bf16_f32 v86, v86, v88
	v_pk_add_f32 v[94:95], v[122:123], v[94:95]
	v_cvt_pk_bf16_f32 v87, v87, v89
	v_add_f32_e32 v94, v94, v95
	v_add_f32_e32 v108, v116, v94
	v_add_u32_e32 v94, s6, v215
	v_cvt_pk_bf16_f32 v88, v90, v92
	v_cvt_pk_bf16_f32 v89, v91, v93
	ds_read_b128 v[134:137], v94 offset:8192
	ds_read_b128 v[138:141], v94 offset:10240
	ds_read_b128 v[142:145], v94 offset:12288
	ds_read_b128 v[170:173], v94 offset:14336
	s_waitcnt lgkmcnt(4)
	v_cvt_pk_bf16_f32 v95, v124, v125
	s_nop 0
	s_waitcnt lgkmcnt(3)
	v_mfma_f32_16x16x32_bf16 v[80:83], v[134:137], v[86:89], v[80:83]
	s_nop 0
	v_cvt_pk_bf16_f32 v96, v96, v98
	v_cvt_pk_bf16_f32 v97, v118, v120
	s_nop 0
	s_waitcnt lgkmcnt(2)
	v_mfma_f32_16x16x32_bf16 v[76:79], v[138:141], v[86:89], v[76:79]
	s_nop 0
	s_nop 0
	s_waitcnt lgkmcnt(1)
	v_mfma_f32_16x16x32_bf16 v[90:93], v[142:145], v[86:89], v[72:75]
	s_nop 2
	s_nop 0
	v_cvt_pk_bf16_f32 v94, v85, v117
	v_add_u32_e32 v85, s6, v216
	ds_read_b128 v[174:177], v85 offset:8192
	ds_read_b128 v[182:185], v85 offset:10240
	ds_read_b128 v[186:189], v85 offset:14336
	ds_read_b128 v[206:209], v85 offset:12288
	s_nop 0
	s_waitcnt lgkmcnt(4)
	v_mfma_f32_16x16x32_bf16 v[86:89], v[170:173], v[86:89], v[68:71]
	s_nop 2
	s_nop 0
	s_nop 0
	s_nop 0
	s_waitcnt lgkmcnt(3)
	v_mfma_f32_16x16x32_bf16 v[68:71], v[174:177], v[94:97], v[80:83]
	s_nop 2
	s_nop 0
	s_nop 0
	s_waitcnt lgkmcnt(2)
	v_mfma_f32_16x16x32_bf16 v[72:75], v[182:185], v[94:97], v[76:79]
	s_nop 2
	s_nop 0
	s_nop 0
	s_waitcnt lgkmcnt(0)
	v_mfma_f32_16x16x32_bf16 v[76:79], v[206:209], v[94:97], v[90:93]
	v_mfma_f32_16x16x32_bf16 v[80:83], v[186:189], v[94:97], v[86:89]
	s_branch .LBB0_1245

.LBB0_1235:
	s_and_b64 vcc, exec, s[52:53]
	s_cbranch_vccz .LBB0_1228
	ds_read_b128 v[134:137], v84
	ds_read_b128 v[138:141], v3
	ds_read_b128 v[142:145], v2
	ds_read_b128 v[170:173], v0
	ds_read_b128 v[174:177], v84 offset:4096
	ds_read_b128 v[182:185], v3 offset:4096
	ds_read_b128 v[186:189], v2 offset:4096
	s_waitcnt lgkmcnt(7)
	s_nop 0
	v_cmp_ge_f32_e64 s[28:29], s76, v92
	s_nop 0
	s_nop 0
	v_cndmask_b32_e64 v36, v92, 0, s[28:29]
	v_xor_b32_e32 v46, 0x80000000, v36
	v_mov_b32_e32 v47, v46
	v_mov_b32_e32 v48, v46
	v_mov_b32_e32 v49, v46
	s_waitcnt vmcnt(3)
	s_nop 0
	s_waitcnt lgkmcnt(6)
	v_mfma_f32_16x16x32_bf16 v[38:41], v[134:137], v[4:7], v[46:49]
	s_waitcnt vmcnt(2)
	s_waitcnt lgkmcnt(5)
	v_mfma_f32_16x16x32_bf16 v[52:55], v[138:141], v[8:11], v[38:41]
	s_nop 0
	s_waitcnt lgkmcnt(4)
	v_mfma_f32_16x16x32_bf16 v[42:45], v[142:145], v[4:7], v[46:49]
	s_nop 3
	s_nop 0
	s_nop 0
	v_max_f32_e32 v37, v55, v55
	v_max_f32_e32 v50, v54, v54
	s_nop 0
	s_waitcnt lgkmcnt(3)
	v_mfma_f32_16x16x32_bf16 v[56:59], v[170:173], v[8:11], v[42:45]
	s_nop 2
	s_nop 0
	s_nop 0
	ds_read_b128 v[94:97], v0 offset:4096
	s_nop 0
	v_max_f32_e32 v37, v50, v37
	s_nop 0
	s_waitcnt lgkmcnt(3)
	v_mfma_f32_16x16x32_bf16 v[38:41], v[174:177], v[4:7], v[46:49]
	v_max3_f32 v37, v52, v53, v37
	s_nop 0
	s_waitcnt lgkmcnt(2)
	v_mfma_f32_16x16x32_bf16 v[60:63], v[182:185], v[8:11], v[38:41]
	v_max3_f32 v42, v57, v58, v59
	v_max3_f32 v37, v37, v56, v42
	s_nop 0
	s_waitcnt lgkmcnt(1)
	v_mfma_f32_16x16x32_bf16 v[38:41], v[186:189], v[4:7], v[46:49]
	s_nop 0
	s_waitcnt lgkmcnt(0)
	v_mfma_f32_16x16x32_bf16 v[64:67], v[94:97], v[8:11], v[38:41]
	s_nop 1
	v_max3_f32 v42, v61, v62, v63
	v_max3_f32 v37, v37, v60, v42
	s_nop 3
	v_max3_f32 v38, v65, v66, v67
	v_max3_f32 v37, v37, v64, v38
	v_cmp_lt_f32_e32 vcc, s76, v37
	s_nop 1
	v_cndmask_b32_e64 v38, 0, 1, vcc
	v_cmp_lt_f32_e32 vcc, s82, v37
	s_nop 1
	v_cndmask_b32_e64 v39, 0, 1, vcc
	v_cndmask_b32_e64 v38, v39, v38, s[28:29]
	v_and_b32_e32 v38, 1, v38
	v_cmp_ne_u32_e32 vcc, 0, v38
	s_cbranch_vccz .LBB0_1249
	v_mov_b32_e32 v38, v37
	s_nop 1
	v_permlane16_swap_b32_e32 v37, v38
	v_max_f32_e32 v38, v38, v38
	v_max_f32_e32 v37, v37, v37
	v_max_f32_e32 v37, v37, v38
	v_mov_b32_e32 v38, v37
	s_nop 1
	v_permlane32_swap_b32_e32 v37, v38
	v_max_f32_e32 v38, v38, v38
	v_max_f32_e32 v37, v37, v37
	v_max_f32_e32 v37, v37, v38
	v_cmp_ge_f32_e32 vcc, s76, v37
	s_and_b64 vcc, s[28:29], vcc
	s_nop 0
	v_cndmask_b32_e64 v38, v37, 0, vcc
	v_max_f32_e32 v37, 0, v37
	v_cndmask_b32_e64 v123, v37, v38, s[28:29]
	v_exp_f32_e64 v96, -v123
	v_add_f32_e32 v36, v36, v123
	v_cndmask_b32_e32 v114, v36, v92, vcc
	v_sub_f32_e32 v95, v52, v123
	v_mul_f32_e32 v94, v93, v96
	v_pk_mul_f32 v[50:51], v[82:83], v[96:97] op_sel_hi:[1,0]
	v_pk_mul_f32 v[48:49], v[80:81], v[96:97] op_sel_hi:[1,0]
	v_pk_mul_f32 v[46:47], v[78:79], v[96:97] op_sel_hi:[1,0]
	v_pk_mul_f32 v[44:45], v[76:77], v[96:97] op_sel_hi:[1,0]
	v_pk_mul_f32 v[42:43], v[74:75], v[96:97] op_sel_hi:[1,0]
	v_pk_mul_f32 v[40:41], v[72:73], v[96:97] op_sel_hi:[1,0]
	v_pk_mul_f32 v[38:39], v[70:71], v[96:97] op_sel_hi:[1,0]
	v_pk_mul_f32 v[36:37], v[68:69], v[96:97] op_sel_hi:[1,0]
	v_sub_f32_e32 v96, v53, v123
	v_sub_f32_e32 v97, v54, v123
	v_sub_f32_e32 v98, v55, v123
	v_sub_f32_e32 v99, v56, v123
	v_sub_f32_e32 v108, v57, v123
	v_sub_f32_e32 v109, v58, v123
	v_sub_f32_e32 v115, v59, v123
	v_sub_f32_e32 v116, v60, v123
	v_sub_f32_e32 v117, v61, v123
	v_sub_f32_e32 v118, v62, v123
	v_sub_f32_e32 v119, v63, v123
	v_sub_f32_e32 v120, v64, v123
	v_sub_f32_e32 v121, v65, v123
	v_sub_f32_e32 v122, v66, v123
	v_sub_f32_e32 v123, v67, v123
	s_cbranch_execnz .LBB0_1239

.LBB0_1239:
	v_exp_f32_e32 v52, v95
	v_exp_f32_e32 v54, v96
	v_exp_f32_e32 v53, v97
	v_exp_f32_e32 v55, v98
	v_exp_f32_e32 v56, v99
	v_exp_f32_e32 v58, v108
	v_exp_f32_e32 v57, v109
	v_exp_f32_e32 v59, v115
	v_exp_f32_e32 v76, v116
	v_exp_f32_e32 v77, v117
	v_exp_f32_e32 v95, v118
	v_exp_f32_e32 v96, v119
	v_pk_add_f32 v[60:61], v[52:53], v[54:55]
	v_exp_f32_e32 v78, v120
	v_exp_f32_e32 v80, v121
	v_exp_f32_e32 v82, v122
	v_exp_f32_e32 v92, v123
	v_add_f32_e32 v60, v60, v61
	v_add_f32_e32 v93, 0, v60
	v_pk_add_f32 v[60:61], v[56:57], v[58:59]
	v_add_f32_e32 v79, v76, v77
	v_pk_add_f32 v[60:61], v[60:61], v[60:61] op_sel_hi:[0,1]
	v_add_f32_e32 v81, v95, v96
	v_mov_b32_e32 v83, v61
	v_pk_add_f32 v[62:63], v[78:79], v[80:81]
	v_pk_add_f32 v[60:61], v[82:83], v[92:93]
	v_add_u32_e32 v64, s6, v215
	v_pk_add_f32 v[60:61], v[62:63], v[60:61]
	v_cvt_pk_bf16_f32 v68, v52, v54
	v_add_f32_e32 v60, v60, v61
	v_add_f32_e32 v109, v94, v60
	v_cvt_pk_bf16_f32 v69, v53, v55
	v_cvt_pk_bf16_f32 v70, v56, v58
	v_cvt_pk_bf16_f32 v71, v57, v59
	ds_read_b128 v[52:55], v64 offset:8192
	s_waitcnt lgkmcnt(1)
	ds_read_b128 v[56:59], v64 offset:10240
	s_nop 0
	ds_read_b128 v[60:63], v64 offset:12288
	s_nop 0
	ds_read_b128 v[64:67], v64 offset:14336
	s_nop 0
	v_cvt_pk_bf16_f32 v78, v78, v80
	v_add_u32_e32 v80, s6, v216
	ds_read_b128 v[174:177], v80 offset:10240
	ds_read_b128 v[182:185], v80 offset:8192
	ds_read_b128 v[186:189], v80 offset:12288
	ds_read_b128 v[206:209], v80 offset:14336
	s_nop 0
	s_waitcnt lgkmcnt(7)
	v_mfma_f32_16x16x32_bf16 v[48:51], v[52:55], v[68:71], v[48:51]
	v_cvt_pk_bf16_f32 v76, v76, v77
	v_cvt_pk_bf16_f32 v77, v95, v96
	v_cvt_pk_bf16_f32 v79, v82, v92
	s_nop 0
	s_waitcnt lgkmcnt(6)
	v_mfma_f32_16x16x32_bf16 v[44:47], v[56:59], v[68:71], v[44:47]
	s_nop 0
	s_waitcnt lgkmcnt(5)
	v_mfma_f32_16x16x32_bf16 v[72:75], v[60:63], v[68:71], v[40:43]
	s_nop 2
	s_nop 0
	s_nop 0
	s_waitcnt lgkmcnt(4)
	v_mfma_f32_16x16x32_bf16 v[68:71], v[64:67], v[68:71], v[36:39]
	s_nop 2
	s_nop 0
	s_nop 0
	s_waitcnt lgkmcnt(3)
	v_mfma_f32_16x16x32_bf16 v[40:43], v[174:177], v[76:79], v[44:47]
	s_nop 2
	s_nop 0
	s_nop 0
	s_waitcnt lgkmcnt(2)
	v_mfma_f32_16x16x32_bf16 v[36:39], v[182:185], v[76:79], v[48:51]
	s_nop 2
	s_nop 0
	s_nop 0
	s_waitcnt lgkmcnt(1)
	v_mfma_f32_16x16x32_bf16 v[44:47], v[186:189], v[76:79], v[72:75]
	s_nop 0
	s_waitcnt lgkmcnt(0)
	v_mfma_f32_16x16x32_bf16 v[48:51], v[206:209], v[76:79], v[68:71]
	s_mov_b64 s[30:31], -1
	s_andn2_b64 vcc, exec, s[48:49]
	v_cmp_ge_f32_e64 s[28:29], s76, v112
	s_cbranch_vccz .LBB0_1229
.LBB0_1240:
	s_and_b64 vcc, exec, s[30:31]
	s_cbranch_vccz .LBB0_1245
	ds_read_b128 v[134:137], v84
	ds_read_b128 v[138:141], v3
	ds_read_b128 v[142:145], v2
	ds_read_b128 v[170:173], v0
	ds_read_b128 v[174:177], v84 offset:4096
	ds_read_b128 v[182:185], v3 offset:4096
	ds_read_b128 v[186:189], v2 offset:4096
	ds_read_b128 v[206:209], v0 offset:4096
	s_waitcnt lgkmcnt(8)
	s_nop 0
	v_cmp_ge_f32_e64 s[28:29], s76, v112
	s_nop 0
	s_nop 0
	v_cndmask_b32_e64 v85, v112, 0, s[28:29]
	v_xor_b32_e32 v80, 0x80000000, v85
	v_mov_b32_e32 v81, v80
	v_mov_b32_e32 v82, v80
	v_mov_b32_e32 v83, v80
	s_waitcnt vmcnt(1)
	s_nop 0
	s_waitcnt lgkmcnt(7)
	v_mfma_f32_16x16x32_bf16 v[68:71], v[134:137], v[12:15], v[80:83]
	s_waitcnt vmcnt(0)
	s_waitcnt lgkmcnt(6)
	v_mfma_f32_16x16x32_bf16 v[68:71], v[138:141], v[16:19], v[68:71]
	s_nop 0
	s_nop 0
	s_waitcnt lgkmcnt(5)
	v_mfma_f32_16x16x32_bf16 v[72:75], v[142:145], v[12:15], v[80:83]
	s_nop 0
	s_waitcnt lgkmcnt(4)
	v_mfma_f32_16x16x32_bf16 v[72:75], v[170:173], v[16:19], v[72:75]
	s_nop 0
	s_nop 0
	s_nop 0
	v_max_f32_e32 v0, v71, v71
	s_nop 0
	s_waitcnt lgkmcnt(3)
	v_mfma_f32_16x16x32_bf16 v[76:79], v[174:177], v[12:15], v[80:83]
	v_max_f32_e32 v2, v70, v70
	v_max_f32_e32 v0, v2, v0
	v_max3_f32 v0, v68, v69, v0
	s_nop 0
	s_waitcnt lgkmcnt(1)
	v_mfma_f32_16x16x32_bf16 v[80:83], v[186:189], v[12:15], v[80:83]
	v_max3_f32 v2, v73, v74, v75
	v_max3_f32 v0, v0, v72, v2
	v_mfma_f32_16x16x32_bf16 v[76:79], v[182:185], v[16:19], v[76:79]
	s_nop 0
	s_waitcnt lgkmcnt(0)
	v_mfma_f32_16x16x32_bf16 v[80:83], v[206:209], v[16:19], v[80:83]
	s_nop 5
	v_max3_f32 v2, v77, v78, v79
	v_max3_f32 v0, v0, v76, v2
	v_max3_f32 v2, v81, v82, v83
	v_max3_f32 v0, v0, v80, v2
	v_cmp_lt_f32_e32 vcc, s76, v0
	s_nop 1
	v_cndmask_b32_e64 v2, 0, 1, vcc
	v_cmp_lt_f32_e32 vcc, s82, v0
	s_nop 1
	v_cndmask_b32_e64 v3, 0, 1, vcc
	v_cndmask_b32_e64 v2, v3, v2, s[28:29]
	v_and_b32_e32 v2, 1, v2
	v_cmp_ne_u32_e32 vcc, 0, v2
	s_cbranch_vccz .LBB0_1250
	v_mov_b32_e32 v2, v0
	s_nop 1
	v_permlane16_swap_b32_e32 v0, v2
	v_max_f32_e32 v2, v2, v2
	v_max_f32_e32 v0, v0, v0
	v_max_f32_e32 v0, v0, v2
	v_mov_b32_e32 v2, v0
	s_nop 1
	v_permlane32_swap_b32_e32 v0, v2
	v_max_f32_e32 v2, v2, v2
	v_max_f32_e32 v0, v0, v0
	v_max_f32_e32 v0, v0, v2
	v_cmp_ge_f32_e32 vcc, s76, v0
	s_and_b64 vcc, s[28:29], vcc
	s_nop 0
	v_cndmask_b32_e64 v2, v0, 0, vcc
	v_max_f32_e32 v0, 0, v0
	v_cndmask_b32_e64 v3, v0, v2, s[28:29]
	v_exp_f32_e64 v2, -v3
	v_add_f32_e32 v0, v85, v3
	v_cndmask_b32_e32 v115, v0, v112, vcc
	v_sub_f32_e32 v108, v68, v3
	v_mul_f32_e32 v0, v113, v2
	v_pk_mul_f32 v[86:87], v[34:35], v[2:3] op_sel_hi:[1,0]
	v_pk_mul_f32 v[84:85], v[32:33], v[2:3] op_sel_hi:[1,0]
	v_pk_mul_f32 v[90:91], v[30:31], v[2:3] op_sel_hi:[1,0]
	v_pk_mul_f32 v[88:89], v[28:29], v[2:3] op_sel_hi:[1,0]
	v_pk_mul_f32 v[98:99], v[26:27], v[2:3] op_sel_hi:[1,0]
	v_pk_mul_f32 v[96:97], v[24:25], v[2:3] op_sel_hi:[1,0]
	v_pk_mul_f32 v[94:95], v[22:23], v[2:3] op_sel_hi:[1,0]
	v_pk_mul_f32 v[92:93], v[20:21], v[2:3] op_sel_hi:[1,0]
	v_sub_f32_e32 v116, v69, v3
	v_sub_f32_e32 v117, v70, v3
	v_sub_f32_e32 v118, v71, v3
	v_sub_f32_e32 v119, v72, v3
	v_sub_f32_e32 v120, v73, v3
	v_sub_f32_e32 v121, v74, v3
	v_sub_f32_e32 v122, v75, v3
	v_sub_f32_e32 v123, v76, v3
	v_sub_f32_e32 v124, v77, v3
	v_sub_f32_e32 v125, v78, v3
	v_sub_f32_e32 v126, v79, v3
	v_sub_f32_e32 v127, v80, v3
	v_sub_f32_e32 v128, v81, v3
	v_sub_f32_e32 v2, v82, v3
	v_sub_f32_e32 v3, v83, v3
	s_cbranch_execnz .LBB0_1244
